# v80 + GEMM K-loop back-edge rotation (asm guide 7.11): counter / pointer SALU updates and the exit compare moved in front of the closing barrier (P1 both instances, P5)
# baseline (speedup 1.0000x reference)
.LBB0_144:
	ds_read_b128 v[146:149], v159
	ds_read_b128 v[150:153], v159 offset:1024
	ds_read_b128 v[154:157], v159 offset:2048
	ds_read_b128 v[166:169], v159 offset:3072
	ds_read_b128 v[170:173], v160
	ds_read_b128 v[174:177], v160 offset:1024
	ds_read_b128 v[178:181], v160 offset:2048
	ds_read_b128 v[182:185], v160 offset:3072
	s_add_u32 s24, s22, 0xfffc0080
	s_addc_u32 s25, s23, -1
	s_cmp_eq_u32 s60, 12
	s_cselect_b32 s29, s50, s25
	s_cselect_b32 s28, s51, s24
	s_cselect_b32 s25, s56, s59
	s_cselect_b32 s24, s57, s58
	v_lshl_add_u64 v[218:219], s[22:23], 0, v[142:143]
	s_add_i32 m0, s37, 0xc000
	ds_read_b128 v[186:189], v161
	ds_read_b128 v[190:193], v161 offset:1024
	ds_read_b128 v[194:197], v161 offset:2048
	ds_read_b128 v[198:201], v161 offset:3072
	ds_read_b128 v[202:205], v161 offset:4096
	ds_read_b128 v[206:209], v161 offset:5120
	ds_read_b128 v[210:213], v161 offset:6144
	ds_read_b128 v[214:217], v161 offset:7168
	global_load_lds_dwordx4 v[218:219], off
	v_lshl_add_u64 v[218:219], s[22:23], 0, v[144:145]
	s_add_i32 m0, s37, 0xe000
	s_nop 0
	global_load_lds_dwordx4 v[218:219], off
	s_waitcnt vmcnt(8)
	s_waitcnt lgkmcnt(0)
	s_barrier
	s_setprio 1
	s_waitcnt lgkmcnt(0)
	v_mfma_f32_16x16x32_bf16 v[126:129], v[146:149], v[186:189], v[126:129]
	v_mfma_f32_16x16x32_bf16 v[122:125], v[154:157], v[186:189], v[122:125]
	v_mfma_f32_16x16x32_bf16 v[110:113], v[146:149], v[194:197], v[110:113]
	v_mfma_f32_16x16x32_bf16 v[106:109], v[154:157], v[194:197], v[106:109]
	v_mfma_f32_16x16x32_bf16 v[94:97], v[146:149], v[202:205], v[94:97]
	v_mfma_f32_16x16x32_bf16 v[90:93], v[154:157], v[202:205], v[90:93]
	v_mfma_f32_16x16x32_bf16 v[78:81], v[146:149], v[210:213], v[78:81]
	v_mfma_f32_16x16x32_bf16 v[74:77], v[154:157], v[210:213], v[74:77]
	v_mfma_f32_16x16x32_bf16 v[126:129], v[150:153], v[190:193], v[126:129]
	v_mfma_f32_16x16x32_bf16 v[122:125], v[166:169], v[190:193], v[122:125]
	v_mfma_f32_16x16x32_bf16 v[110:113], v[150:153], v[198:201], v[110:113]
	v_mfma_f32_16x16x32_bf16 v[106:109], v[166:169], v[198:201], v[106:109]
	v_mfma_f32_16x16x32_bf16 v[94:97], v[150:153], v[206:209], v[94:97]
	v_mfma_f32_16x16x32_bf16 v[90:93], v[166:169], v[206:209], v[90:93]
	v_mfma_f32_16x16x32_bf16 v[78:81], v[150:153], v[214:217], v[78:81]
	v_mfma_f32_16x16x32_bf16 v[74:77], v[166:169], v[214:217], v[74:77]
	s_setprio 0
	s_setprio 1
	v_mfma_f32_16x16x32_bf16 v[118:121], v[170:173], v[186:189], v[118:121]
	v_mfma_f32_16x16x32_bf16 v[114:117], v[178:181], v[186:189], v[114:117]
	v_mfma_f32_16x16x32_bf16 v[102:105], v[170:173], v[194:197], v[102:105]
	v_mfma_f32_16x16x32_bf16 v[98:101], v[178:181], v[194:197], v[98:101]
	v_mfma_f32_16x16x32_bf16 v[86:89], v[170:173], v[202:205], v[86:89]
	v_mfma_f32_16x16x32_bf16 v[82:85], v[178:181], v[202:205], v[82:85]
	v_mfma_f32_16x16x32_bf16 v[70:73], v[170:173], v[210:213], v[70:73]
	v_mfma_f32_16x16x32_bf16 v[66:69], v[178:181], v[210:213], v[66:69]
	v_mfma_f32_16x16x32_bf16 v[118:121], v[174:177], v[190:193], v[118:121]
	v_mfma_f32_16x16x32_bf16 v[114:117], v[182:185], v[190:193], v[114:117]
	v_mfma_f32_16x16x32_bf16 v[102:105], v[174:177], v[198:201], v[102:105]
	v_mfma_f32_16x16x32_bf16 v[98:101], v[182:185], v[198:201], v[98:101]
	v_mfma_f32_16x16x32_bf16 v[86:89], v[174:177], v[206:209], v[86:89]
	v_mfma_f32_16x16x32_bf16 v[82:85], v[182:185], v[206:209], v[82:85]
	v_mfma_f32_16x16x32_bf16 v[70:73], v[174:177], v[214:217], v[70:73]
	v_mfma_f32_16x16x32_bf16 v[66:69], v[182:185], v[214:217], v[66:69]
	s_setprio 0
	s_barrier
	s_add_i32 s61, s47, s31
	v_lshl_add_u64 v[218:219], s[24:25], 0, v[134:135]
	s_mov_b32 m0, s61
	ds_read_b128 v[186:189], v161 offset:16384
	ds_read_b128 v[190:193], v161 offset:17408
	ds_read_b128 v[194:197], v161 offset:18432
	ds_read_b128 v[198:201], v161 offset:19456
	ds_read_b128 v[202:205], v161 offset:20480
	ds_read_b128 v[206:209], v161 offset:21504
	ds_read_b128 v[210:213], v161 offset:22528
	ds_read_b128 v[214:217], v161 offset:23552
	global_load_lds_dwordx4 v[218:219], off
	s_add_i32 m0, s61, 0x2000
	s_add_u32 s68, s24, 0x40000
	v_lshl_add_u64 v[220:221], s[24:25], 0, v[130:131]
	s_addc_u32 s69, s25, 0
	s_add_i32 s61, s48, s31
	global_load_lds_dwordx4 v[220:221], off
	v_lshl_add_u64 v[222:223], s[68:69], 0, v[134:135]
	s_mov_b32 m0, s61
	v_lshl_add_u64 v[224:225], s[28:29], 0, v[132:133]
	global_load_lds_dwordx4 v[222:223], off
	v_lshl_add_u64 v[222:223], s[68:69], 0, v[130:131]
	s_add_i32 m0, s61, 0x2000
	s_nop 0
	global_load_lds_dwordx4 v[222:223], off
	v_lshl_add_u64 v[222:223], s[28:29], 0, v[136:137]
	s_mov_b32 m0, s37
	s_nop 0
	global_load_lds_dwordx4 v[222:223], off
	s_mov_b32 m0, s38
	s_nop 0
	global_load_lds_dwordx4 v[224:225], off
	s_waitcnt vmcnt(8)
	s_waitcnt lgkmcnt(0)
	s_barrier
	s_setprio 1
	s_waitcnt lgkmcnt(0)
	v_mfma_f32_16x16x32_bf16 v[62:65], v[146:149], v[186:189], v[62:65]
	v_mfma_f32_16x16x32_bf16 v[58:61], v[154:157], v[186:189], v[58:61]
	v_mfma_f32_16x16x32_bf16 v[46:49], v[146:149], v[194:197], v[46:49]
	v_mfma_f32_16x16x32_bf16 v[42:45], v[154:157], v[194:197], v[42:45]
	v_mfma_f32_16x16x32_bf16 v[30:33], v[146:149], v[202:205], v[30:33]
	v_mfma_f32_16x16x32_bf16 v[26:29], v[154:157], v[202:205], v[26:29]
	v_mfma_f32_16x16x32_bf16 v[14:17], v[146:149], v[210:213], v[14:17]
	v_mfma_f32_16x16x32_bf16 v[10:13], v[154:157], v[210:213], v[10:13]
	v_mfma_f32_16x16x32_bf16 v[62:65], v[150:153], v[190:193], v[62:65]
	v_mfma_f32_16x16x32_bf16 v[58:61], v[166:169], v[190:193], v[58:61]
	v_mfma_f32_16x16x32_bf16 v[46:49], v[150:153], v[198:201], v[46:49]
	v_mfma_f32_16x16x32_bf16 v[42:45], v[166:169], v[198:201], v[42:45]
	v_mfma_f32_16x16x32_bf16 v[30:33], v[150:153], v[206:209], v[30:33]
	v_mfma_f32_16x16x32_bf16 v[26:29], v[166:169], v[206:209], v[26:29]
	v_mfma_f32_16x16x32_bf16 v[14:17], v[150:153], v[214:217], v[14:17]
	v_mfma_f32_16x16x32_bf16 v[10:13], v[166:169], v[214:217], v[10:13]
	s_setprio 0
	s_setprio 1
	v_mfma_f32_16x16x32_bf16 v[54:57], v[170:173], v[186:189], v[54:57]
	v_mfma_f32_16x16x32_bf16 v[50:53], v[178:181], v[186:189], v[50:53]
	v_mfma_f32_16x16x32_bf16 v[38:41], v[170:173], v[194:197], v[38:41]
	v_mfma_f32_16x16x32_bf16 v[34:37], v[178:181], v[194:197], v[34:37]
	v_mfma_f32_16x16x32_bf16 v[22:25], v[170:173], v[202:205], v[22:25]
	v_mfma_f32_16x16x32_bf16 v[18:21], v[178:181], v[202:205], v[18:21]
	v_mfma_f32_16x16x32_bf16 v[6:9], v[170:173], v[210:213], v[6:9]
	v_mfma_f32_16x16x32_bf16 v[2:5], v[178:181], v[210:213], v[2:5]
	v_mfma_f32_16x16x32_bf16 v[54:57], v[174:177], v[190:193], v[54:57]
	v_mfma_f32_16x16x32_bf16 v[50:53], v[182:185], v[190:193], v[50:53]
	v_mfma_f32_16x16x32_bf16 v[38:41], v[174:177], v[198:201], v[38:41]
	v_mfma_f32_16x16x32_bf16 v[34:37], v[182:185], v[198:201], v[34:37]
	v_mfma_f32_16x16x32_bf16 v[22:25], v[174:177], v[206:209], v[22:25]
	v_mfma_f32_16x16x32_bf16 v[18:21], v[182:185], v[206:209], v[18:21]
	v_mfma_f32_16x16x32_bf16 v[6:9], v[174:177], v[214:217], v[6:9]
	v_mfma_f32_16x16x32_bf16 v[2:5], v[182:185], v[214:217], v[2:5]
	s_setprio 0
	s_barrier
	s_add_i32 s61, 0, 0x18000
	v_add_u32_e32 v138, s61, v141
	s_add_i32 s68, 0, 0x1c000
	ds_read_b128 v[146:149], v138
	ds_read_b128 v[150:153], v138 offset:1024
	ds_read_b128 v[154:157], v138 offset:2048
	ds_read_b128 v[166:169], v138 offset:3072
	v_add_u32_e32 v138, s68, v141
	ds_read_b128 v[170:173], v138
	ds_read_b128 v[174:177], v138 offset:1024
	ds_read_b128 v[178:181], v138 offset:2048
	ds_read_b128 v[182:185], v138 offset:3072
	s_add_u32 s28, s28, 0x40000
	s_addc_u32 s29, s29, 0
	s_mov_b32 m0, s39
	v_lshl_add_u64 v[226:227], s[28:29], 0, v[136:137]
	ds_read_b128 v[186:189], v161 offset:32768
	ds_read_b128 v[190:193], v161 offset:33792
	ds_read_b128 v[194:197], v161 offset:34816
	ds_read_b128 v[198:201], v161 offset:35840
	ds_read_b128 v[202:205], v161 offset:36864
	ds_read_b128 v[206:209], v161 offset:37888
	ds_read_b128 v[210:213], v161 offset:38912
	ds_read_b128 v[214:217], v161 offset:39936
	global_load_lds_dwordx4 v[226:227], off
	v_lshl_add_u64 v[226:227], s[28:29], 0, v[132:133]
	s_mov_b32 m0, s40
	s_nop 0
	global_load_lds_dwordx4 v[226:227], off
	s_waitcnt vmcnt(8)
	s_waitcnt lgkmcnt(0)
	s_barrier
	s_setprio 1
	s_waitcnt lgkmcnt(0)
	v_mfma_f32_16x16x32_bf16 v[126:129], v[146:149], v[186:189], v[126:129]
	v_mfma_f32_16x16x32_bf16 v[122:125], v[154:157], v[186:189], v[122:125]
	v_mfma_f32_16x16x32_bf16 v[110:113], v[146:149], v[194:197], v[110:113]
	v_mfma_f32_16x16x32_bf16 v[106:109], v[154:157], v[194:197], v[106:109]
	v_mfma_f32_16x16x32_bf16 v[94:97], v[146:149], v[202:205], v[94:97]
	v_mfma_f32_16x16x32_bf16 v[90:93], v[154:157], v[202:205], v[90:93]
	v_mfma_f32_16x16x32_bf16 v[78:81], v[146:149], v[210:213], v[78:81]
	v_mfma_f32_16x16x32_bf16 v[74:77], v[154:157], v[210:213], v[74:77]
	v_mfma_f32_16x16x32_bf16 v[126:129], v[150:153], v[190:193], v[126:129]
	v_mfma_f32_16x16x32_bf16 v[122:125], v[166:169], v[190:193], v[122:125]
	v_mfma_f32_16x16x32_bf16 v[110:113], v[150:153], v[198:201], v[110:113]
	v_mfma_f32_16x16x32_bf16 v[106:109], v[166:169], v[198:201], v[106:109]
	v_mfma_f32_16x16x32_bf16 v[94:97], v[150:153], v[206:209], v[94:97]
	v_mfma_f32_16x16x32_bf16 v[90:93], v[166:169], v[206:209], v[90:93]
	v_mfma_f32_16x16x32_bf16 v[78:81], v[150:153], v[214:217], v[78:81]
	v_mfma_f32_16x16x32_bf16 v[74:77], v[166:169], v[214:217], v[74:77]
	s_setprio 0
	s_setprio 1
	v_mfma_f32_16x16x32_bf16 v[118:121], v[170:173], v[186:189], v[118:121]
	v_mfma_f32_16x16x32_bf16 v[114:117], v[178:181], v[186:189], v[114:117]
	v_mfma_f32_16x16x32_bf16 v[102:105], v[170:173], v[194:197], v[102:105]
	v_mfma_f32_16x16x32_bf16 v[98:101], v[178:181], v[194:197], v[98:101]
	v_mfma_f32_16x16x32_bf16 v[86:89], v[170:173], v[202:205], v[86:89]
	v_mfma_f32_16x16x32_bf16 v[82:85], v[178:181], v[202:205], v[82:85]
	v_mfma_f32_16x16x32_bf16 v[70:73], v[170:173], v[210:213], v[70:73]
	v_mfma_f32_16x16x32_bf16 v[66:69], v[178:181], v[210:213], v[66:69]
	v_mfma_f32_16x16x32_bf16 v[118:121], v[174:177], v[190:193], v[118:121]
	v_mfma_f32_16x16x32_bf16 v[114:117], v[182:185], v[190:193], v[114:117]
	v_mfma_f32_16x16x32_bf16 v[102:105], v[174:177], v[198:201], v[102:105]
	v_mfma_f32_16x16x32_bf16 v[98:101], v[182:185], v[198:201], v[98:101]
	v_mfma_f32_16x16x32_bf16 v[86:89], v[174:177], v[206:209], v[86:89]
	v_mfma_f32_16x16x32_bf16 v[82:85], v[182:185], v[206:209], v[82:85]
	v_mfma_f32_16x16x32_bf16 v[70:73], v[174:177], v[214:217], v[70:73]
	v_mfma_f32_16x16x32_bf16 v[66:69], v[182:185], v[214:217], v[66:69]
	s_setprio 0
	s_barrier
	s_add_i32 s28, s61, s31
	v_lshl_add_u64 v[218:219], v[218:219], 0, s[6:7]
	s_mov_b32 m0, s28
	ds_read_b128 v[186:189], v161 offset:49152
	ds_read_b128 v[190:193], v161 offset:50176
	ds_read_b128 v[194:197], v161 offset:51200
	ds_read_b128 v[198:201], v161 offset:52224
	ds_read_b128 v[202:205], v161 offset:53248
	ds_read_b128 v[206:209], v161 offset:54272
	ds_read_b128 v[210:213], v161 offset:55296
	ds_read_b128 v[214:217], v161 offset:56320
	global_load_lds_dwordx4 v[218:219], off
	s_add_i32 m0, s28, 0x2000
	s_add_u32 s24, s24, 0x40080
	v_lshl_add_u64 v[218:219], v[220:221], 0, s[6:7]
	s_addc_u32 s25, s25, 0
	s_add_i32 s28, s68, s31
	global_load_lds_dwordx4 v[218:219], off
	v_lshl_add_u64 v[218:219], s[24:25], 0, v[134:135]
	s_mov_b32 m0, s28
	s_nop 0
	global_load_lds_dwordx4 v[218:219], off
	v_lshl_add_u64 v[218:219], s[24:25], 0, v[130:131]
	s_add_i32 m0, s28, 0x2000
	s_nop 0
	global_load_lds_dwordx4 v[218:219], off
	v_lshl_add_u64 v[218:219], v[222:223], 0, s[6:7]
	s_mov_b32 m0, s42
	s_nop 0
	global_load_lds_dwordx4 v[218:219], off
	v_lshl_add_u64 v[218:219], v[224:225], 0, s[6:7]
	s_mov_b32 m0, s43
	s_nop 0
	global_load_lds_dwordx4 v[218:219], off
	s_waitcnt vmcnt(8)
	s_waitcnt lgkmcnt(0)
	s_barrier
	s_setprio 1
	s_waitcnt lgkmcnt(0)
	v_mfma_f32_16x16x32_bf16 v[62:65], v[146:149], v[186:189], v[62:65]
	v_mfma_f32_16x16x32_bf16 v[58:61], v[154:157], v[186:189], v[58:61]
	v_mfma_f32_16x16x32_bf16 v[46:49], v[146:149], v[194:197], v[46:49]
	v_mfma_f32_16x16x32_bf16 v[42:45], v[154:157], v[194:197], v[42:45]
	v_mfma_f32_16x16x32_bf16 v[30:33], v[146:149], v[202:205], v[30:33]
	v_mfma_f32_16x16x32_bf16 v[26:29], v[154:157], v[202:205], v[26:29]
	v_mfma_f32_16x16x32_bf16 v[14:17], v[146:149], v[210:213], v[14:17]
	v_mfma_f32_16x16x32_bf16 v[10:13], v[154:157], v[210:213], v[10:13]
	v_mfma_f32_16x16x32_bf16 v[62:65], v[150:153], v[190:193], v[62:65]
	v_mfma_f32_16x16x32_bf16 v[58:61], v[166:169], v[190:193], v[58:61]
	v_mfma_f32_16x16x32_bf16 v[46:49], v[150:153], v[198:201], v[46:49]
	v_mfma_f32_16x16x32_bf16 v[42:45], v[166:169], v[198:201], v[42:45]
	v_mfma_f32_16x16x32_bf16 v[30:33], v[150:153], v[206:209], v[30:33]
	v_mfma_f32_16x16x32_bf16 v[26:29], v[166:169], v[206:209], v[26:29]
	v_mfma_f32_16x16x32_bf16 v[14:17], v[150:153], v[214:217], v[14:17]
	v_mfma_f32_16x16x32_bf16 v[10:13], v[166:169], v[214:217], v[10:13]
	s_setprio 0
	s_setprio 1
	v_mfma_f32_16x16x32_bf16 v[54:57], v[170:173], v[186:189], v[54:57]
	v_mfma_f32_16x16x32_bf16 v[50:53], v[178:181], v[186:189], v[50:53]
	v_mfma_f32_16x16x32_bf16 v[38:41], v[170:173], v[194:197], v[38:41]
	v_mfma_f32_16x16x32_bf16 v[34:37], v[178:181], v[194:197], v[34:37]
	v_mfma_f32_16x16x32_bf16 v[22:25], v[170:173], v[202:205], v[22:25]
	v_mfma_f32_16x16x32_bf16 v[18:21], v[178:181], v[202:205], v[18:21]
	v_mfma_f32_16x16x32_bf16 v[6:9], v[170:173], v[210:213], v[6:9]
	v_mfma_f32_16x16x32_bf16 v[2:5], v[178:181], v[210:213], v[2:5]
	v_mfma_f32_16x16x32_bf16 v[54:57], v[174:177], v[190:193], v[54:57]
	v_mfma_f32_16x16x32_bf16 v[50:53], v[182:185], v[190:193], v[50:53]
	v_mfma_f32_16x16x32_bf16 v[38:41], v[174:177], v[198:201], v[38:41]
	v_mfma_f32_16x16x32_bf16 v[34:37], v[182:185], v[198:201], v[34:37]
	v_mfma_f32_16x16x32_bf16 v[22:25], v[174:177], v[206:209], v[22:25]
	v_mfma_f32_16x16x32_bf16 v[18:21], v[182:185], v[206:209], v[18:21]
	v_mfma_f32_16x16x32_bf16 v[6:9], v[174:177], v[214:217], v[6:9]
	v_mfma_f32_16x16x32_bf16 v[2:5], v[182:185], v[214:217], v[2:5]
	s_add_i32 s60, s60, 2
	s_add_u32 s22, s22, 0x100
	s_addc_u32 s23, s23, 0
	s_add_u32 s58, s58, 0x100
	s_addc_u32 s59, s59, 0
	s_cmp_gt_u32 s60, 13
	s_setprio 0
	s_barrier
	s_cbranch_scc0 .LBB0_144
	s_and_b64 vcc, exec, s[8:9]
	s_cbranch_vccz .LBB0_147
	s_barrier

.Lmy_w2_done:
	s_mov_b32 s99, 0
	s_waitcnt lgkmcnt(0)
	s_barrier
	s_setprio 1
	s_waitcnt lgkmcnt(0)
	v_mfma_f32_16x16x32_bf16 v[62:65], v[130:133], v[192:195], v[62:65]
	v_mfma_f32_16x16x32_bf16 v[58:61], v[152:155], v[192:195], v[58:61]
	v_mfma_f32_16x16x32_bf16 v[50:53], v[130:133], v[200:203], v[50:53]
	v_mfma_f32_16x16x32_bf16 v[42:45], v[152:155], v[200:203], v[42:45]
	v_mfma_f32_16x16x32_bf16 v[34:37], v[130:133], v[208:211], v[34:37]
	v_mfma_f32_16x16x32_bf16 v[26:29], v[152:155], v[208:211], v[26:29]
	v_mfma_f32_16x16x32_bf16 v[18:21], v[130:133], v[216:219], v[18:21]
	v_mfma_f32_16x16x32_bf16 v[10:13], v[152:155], v[216:219], v[10:13]
	v_mfma_f32_16x16x32_bf16 v[62:65], v[134:137], v[196:199], v[62:65]
	v_mfma_f32_16x16x32_bf16 v[58:61], v[156:159], v[196:199], v[58:61]
	v_mfma_f32_16x16x32_bf16 v[50:53], v[134:137], v[204:207], v[50:53]
	v_mfma_f32_16x16x32_bf16 v[42:45], v[156:159], v[204:207], v[42:45]
	v_mfma_f32_16x16x32_bf16 v[34:37], v[134:137], v[212:215], v[34:37]
	v_mfma_f32_16x16x32_bf16 v[26:29], v[156:159], v[212:215], v[26:29]
	v_mfma_f32_16x16x32_bf16 v[18:21], v[134:137], v[220:223], v[18:21]
	v_mfma_f32_16x16x32_bf16 v[10:13], v[156:159], v[220:223], v[10:13]
	s_setprio 0
	s_setprio 1
	v_mfma_f32_16x16x32_bf16 v[54:57], v[176:179], v[192:195], v[54:57]
	v_mfma_f32_16x16x32_bf16 v[46:49], v[184:187], v[192:195], v[46:49]
	v_mfma_f32_16x16x32_bf16 v[38:41], v[176:179], v[200:203], v[38:41]
	v_mfma_f32_16x16x32_bf16 v[30:33], v[184:187], v[200:203], v[30:33]
	v_mfma_f32_16x16x32_bf16 v[22:25], v[176:179], v[208:211], v[22:25]
	v_mfma_f32_16x16x32_bf16 v[14:17], v[184:187], v[208:211], v[14:17]
	v_mfma_f32_16x16x32_bf16 v[6:9], v[176:179], v[216:219], v[6:9]
	v_mfma_f32_16x16x32_bf16 v[2:5], v[184:187], v[216:219], v[2:5]
	v_mfma_f32_16x16x32_bf16 v[54:57], v[180:183], v[196:199], v[54:57]
	v_mfma_f32_16x16x32_bf16 v[46:49], v[188:191], v[196:199], v[46:49]
	v_mfma_f32_16x16x32_bf16 v[38:41], v[180:183], v[204:207], v[38:41]
	v_mfma_f32_16x16x32_bf16 v[30:33], v[188:191], v[204:207], v[30:33]
	v_mfma_f32_16x16x32_bf16 v[22:25], v[180:183], v[212:215], v[22:25]
	v_mfma_f32_16x16x32_bf16 v[14:17], v[188:191], v[212:215], v[14:17]
	v_mfma_f32_16x16x32_bf16 v[6:9], v[180:183], v[220:223], v[6:9]
	v_mfma_f32_16x16x32_bf16 v[2:5], v[188:191], v[220:223], v[2:5]
	s_setprio 0
	s_barrier
	s_add_i32 s24, 0, 0x18000
	v_add_u32_e32 v146, s24, v162
	s_add_i32 s25, 0, 0x1c000
	ds_read_b128 v[130:133], v146
	ds_read_b128 v[134:137], v146 offset:1024
	ds_read_b128 v[152:155], v146 offset:2048
	ds_read_b128 v[156:159], v146 offset:3072
	v_add_u32_e32 v146, s25, v162
	ds_read_b128 v[176:179], v146
	ds_read_b128 v[180:183], v146 offset:1024
	ds_read_b128 v[184:187], v146 offset:2048
	ds_read_b128 v[188:191], v146 offset:3072
	s_add_u32 s6, s6, 0x40000
	s_addc_u32 s7, s7, 0
	s_mov_b32 m0, s36
	v_lshl_add_u64 v[230:231], s[6:7], 0, v[138:139]
	ds_read_b128 v[192:195], v168 offset:32768
	ds_read_b128 v[196:199], v168 offset:33792
	ds_read_b128 v[200:203], v168 offset:34816
	ds_read_b128 v[204:207], v168 offset:35840
	ds_read_b128 v[208:211], v168 offset:36864
	ds_read_b128 v[212:215], v168 offset:37888
	ds_read_b128 v[216:219], v168 offset:38912
	ds_read_b128 v[220:223], v168 offset:39936
	global_load_lds_dwordx4 v[230:231], off
	v_lshl_add_u64 v[230:231], s[6:7], 0, v[142:143]
	s_mov_b32 m0, s37
	s_nop 0
	global_load_lds_dwordx4 v[230:231], off
	s_waitcnt vmcnt(8)
	s_waitcnt lgkmcnt(0)
	s_barrier
	s_setprio 1
	s_waitcnt lgkmcnt(0)
	v_mfma_f32_16x16x32_bf16 v[126:129], v[130:133], v[192:195], v[126:129]
	v_mfma_f32_16x16x32_bf16 v[122:125], v[152:155], v[192:195], v[122:125]
	v_mfma_f32_16x16x32_bf16 v[114:117], v[130:133], v[200:203], v[114:117]
	v_mfma_f32_16x16x32_bf16 v[106:109], v[152:155], v[200:203], v[106:109]
	v_mfma_f32_16x16x32_bf16 v[98:101], v[130:133], v[208:211], v[98:101]
	v_mfma_f32_16x16x32_bf16 v[90:93], v[152:155], v[208:211], v[90:93]
	v_mfma_f32_16x16x32_bf16 v[82:85], v[130:133], v[216:219], v[82:85]
	v_mfma_f32_16x16x32_bf16 v[74:77], v[152:155], v[216:219], v[74:77]
	v_mfma_f32_16x16x32_bf16 v[126:129], v[134:137], v[196:199], v[126:129]
	v_mfma_f32_16x16x32_bf16 v[122:125], v[156:159], v[196:199], v[122:125]
	v_mfma_f32_16x16x32_bf16 v[114:117], v[134:137], v[204:207], v[114:117]
	v_mfma_f32_16x16x32_bf16 v[106:109], v[156:159], v[204:207], v[106:109]
	v_mfma_f32_16x16x32_bf16 v[98:101], v[134:137], v[212:215], v[98:101]
	v_mfma_f32_16x16x32_bf16 v[90:93], v[156:159], v[212:215], v[90:93]
	v_mfma_f32_16x16x32_bf16 v[82:85], v[134:137], v[220:223], v[82:85]
	v_mfma_f32_16x16x32_bf16 v[74:77], v[156:159], v[220:223], v[74:77]
	s_setprio 0
	s_setprio 1
	v_mfma_f32_16x16x32_bf16 v[118:121], v[176:179], v[192:195], v[118:121]
	v_mfma_f32_16x16x32_bf16 v[110:113], v[184:187], v[192:195], v[110:113]
	v_mfma_f32_16x16x32_bf16 v[102:105], v[176:179], v[200:203], v[102:105]
	v_mfma_f32_16x16x32_bf16 v[94:97], v[184:187], v[200:203], v[94:97]
	v_mfma_f32_16x16x32_bf16 v[86:89], v[176:179], v[208:211], v[86:89]
	v_mfma_f32_16x16x32_bf16 v[78:81], v[184:187], v[208:211], v[78:81]
	v_mfma_f32_16x16x32_bf16 v[70:73], v[176:179], v[216:219], v[70:73]
	v_mfma_f32_16x16x32_bf16 v[66:69], v[184:187], v[216:219], v[66:69]
	v_mfma_f32_16x16x32_bf16 v[118:121], v[180:183], v[196:199], v[118:121]
	v_mfma_f32_16x16x32_bf16 v[110:113], v[188:191], v[196:199], v[110:113]
	v_mfma_f32_16x16x32_bf16 v[102:105], v[180:183], v[204:207], v[102:105]
	v_mfma_f32_16x16x32_bf16 v[94:97], v[188:191], v[204:207], v[94:97]
	v_mfma_f32_16x16x32_bf16 v[86:89], v[180:183], v[212:215], v[86:89]
	v_mfma_f32_16x16x32_bf16 v[78:81], v[188:191], v[212:215], v[78:81]
	v_mfma_f32_16x16x32_bf16 v[70:73], v[180:183], v[220:223], v[70:73]
	v_mfma_f32_16x16x32_bf16 v[66:69], v[188:191], v[220:223], v[66:69]
	s_setprio 0
	s_barrier
	s_add_i32 s6, s24, s28
	v_lshl_add_u64 v[160:161], v[160:161], 0, s[18:19]
	s_mov_b32 m0, s6
	ds_read_b128 v[192:195], v168 offset:49152
	ds_read_b128 v[196:199], v168 offset:50176
	ds_read_b128 v[200:203], v168 offset:51200
	ds_read_b128 v[204:207], v168 offset:52224
	ds_read_b128 v[208:211], v168 offset:53248
	ds_read_b128 v[212:215], v168 offset:54272
	ds_read_b128 v[216:219], v168 offset:55296
	ds_read_b128 v[220:223], v168 offset:56320
	global_load_lds_dwordx4 v[160:161], off
	s_add_i32 m0, s6, 0x2000
	s_add_u32 s4, s4, 0x40080
	v_lshl_add_u64 v[160:161], v[224:225], 0, s[18:19]
	s_addc_u32 s5, s5, 0
	s_add_i32 s6, s25, s28
	global_load_lds_dwordx4 v[160:161], off
	v_lshl_add_u64 v[160:161], s[4:5], 0, v[140:141]
	s_mov_b32 m0, s6
	s_nop 0
	global_load_lds_dwordx4 v[160:161], off
	v_lshl_add_u64 v[160:161], s[4:5], 0, v[144:145]
	s_add_i32 m0, s6, 0x2000
	s_nop 0
	global_load_lds_dwordx4 v[160:161], off
	v_lshl_add_u64 v[160:161], v[226:227], 0, s[18:19]
	s_mov_b32 m0, s41
	s_nop 0
	global_load_lds_dwordx4 v[160:161], off
	v_lshl_add_u64 v[160:161], v[228:229], 0, s[18:19]
	s_mov_b32 m0, s46
	s_nop 0
	global_load_lds_dwordx4 v[160:161], off
	s_waitcnt vmcnt(8)
	s_waitcnt lgkmcnt(0)
	s_barrier
	s_setprio 1
	s_waitcnt lgkmcnt(0)
	v_mfma_f32_16x16x32_bf16 v[62:65], v[130:133], v[192:195], v[62:65]
	v_mfma_f32_16x16x32_bf16 v[58:61], v[152:155], v[192:195], v[58:61]
	v_mfma_f32_16x16x32_bf16 v[50:53], v[130:133], v[200:203], v[50:53]
	v_mfma_f32_16x16x32_bf16 v[42:45], v[152:155], v[200:203], v[42:45]
	v_mfma_f32_16x16x32_bf16 v[34:37], v[130:133], v[208:211], v[34:37]
	v_mfma_f32_16x16x32_bf16 v[26:29], v[152:155], v[208:211], v[26:29]
	v_mfma_f32_16x16x32_bf16 v[18:21], v[130:133], v[216:219], v[18:21]
	v_mfma_f32_16x16x32_bf16 v[10:13], v[152:155], v[216:219], v[10:13]
	v_mfma_f32_16x16x32_bf16 v[62:65], v[134:137], v[196:199], v[62:65]
	v_mfma_f32_16x16x32_bf16 v[58:61], v[156:159], v[196:199], v[58:61]
	v_mfma_f32_16x16x32_bf16 v[50:53], v[134:137], v[204:207], v[50:53]
	v_mfma_f32_16x16x32_bf16 v[42:45], v[156:159], v[204:207], v[42:45]
	v_mfma_f32_16x16x32_bf16 v[34:37], v[134:137], v[212:215], v[34:37]
	v_mfma_f32_16x16x32_bf16 v[26:29], v[156:159], v[212:215], v[26:29]
	v_mfma_f32_16x16x32_bf16 v[18:21], v[134:137], v[220:223], v[18:21]
	v_mfma_f32_16x16x32_bf16 v[10:13], v[156:159], v[220:223], v[10:13]
	s_setprio 0
	s_setprio 1
	v_mfma_f32_16x16x32_bf16 v[54:57], v[176:179], v[192:195], v[54:57]
	v_mfma_f32_16x16x32_bf16 v[46:49], v[184:187], v[192:195], v[46:49]
	v_mfma_f32_16x16x32_bf16 v[38:41], v[176:179], v[200:203], v[38:41]
	v_mfma_f32_16x16x32_bf16 v[30:33], v[184:187], v[200:203], v[30:33]
	v_mfma_f32_16x16x32_bf16 v[22:25], v[176:179], v[208:211], v[22:25]
	v_mfma_f32_16x16x32_bf16 v[14:17], v[184:187], v[208:211], v[14:17]
	v_mfma_f32_16x16x32_bf16 v[6:9], v[176:179], v[216:219], v[6:9]
	v_mfma_f32_16x16x32_bf16 v[2:5], v[184:187], v[216:219], v[2:5]
	v_mfma_f32_16x16x32_bf16 v[54:57], v[180:183], v[196:199], v[54:57]
	v_mfma_f32_16x16x32_bf16 v[46:49], v[188:191], v[196:199], v[46:49]
	v_mfma_f32_16x16x32_bf16 v[38:41], v[180:183], v[204:207], v[38:41]
	v_mfma_f32_16x16x32_bf16 v[30:33], v[188:191], v[204:207], v[30:33]
	v_mfma_f32_16x16x32_bf16 v[22:25], v[180:183], v[212:215], v[22:25]
	v_mfma_f32_16x16x32_bf16 v[14:17], v[188:191], v[212:215], v[14:17]
	v_mfma_f32_16x16x32_bf16 v[6:9], v[180:183], v[220:223], v[6:9]
	v_mfma_f32_16x16x32_bf16 v[2:5], v[188:191], v[220:223], v[2:5]
	s_add_i32 s23, s23, 2
	s_add_u32 s0, s0, 0x100
	s_addc_u32 s1, s1, 0
	s_add_u32 s13, s13, 0x100
	s_addc_u32 s22, s22, 0
	s_cmp_gt_u32 s23, 13
	s_setprio 0
	s_barrier
	s_cbranch_scc0 .LBB0_260
	s_and_b64 vcc, exec, s[20:21]
	s_cbranch_vccnz .LBB0_265
	v_lshl_add_u32 v152, s12, 8, v1
	s_cmp_gt_i32 s86, 15
	s_mov_b64 s[0:1], -1
	s_cbranch_scc1 .LBB0_266

.LBB0_1174:
	v_add_u32_e32 v147, s43, v1
	ds_read_b128 v[148:151], v147
	ds_read_b128 v[152:155], v147 offset:1024
	ds_read_b128 v[156:159], v147 offset:2048
	ds_read_b128 v[160:163], v147 offset:3072
	v_add_u32_e32 v147, s44, v1
	s_add_u32 s24, s10, s22
	ds_read_b128 v[164:167], v147
	ds_read_b128 v[168:171], v147 offset:1024
	ds_read_b128 v[172:175], v147 offset:2048
	ds_read_b128 v[176:179], v147 offset:3072
	s_addc_u32 s25, s11, s23
	s_add_u32 s24, s24, 0x100
	s_addc_u32 s25, s25, 0
	s_add_u32 s51, s46, s22
	s_addc_u32 s52, s47, s23
	s_cmpk_eq_i32 s22, 0xf00
	s_cselect_b32 s29, s17, s25
	s_cselect_b32 s28, s48, s24
	s_cselect_b32 s25, s15, s52
	s_cselect_b32 s24, s49, s51
	v_lshl_add_u64 v[212:213], v[142:143], 0, s[22:23]
	s_add_i32 m0, s9, 0xc000
	ds_read_b128 v[180:183], v146
	ds_read_b128 v[184:187], v146 offset:1024
	ds_read_b128 v[188:191], v146 offset:2048
	ds_read_b128 v[192:195], v146 offset:3072
	ds_read_b128 v[196:199], v146 offset:4096
	ds_read_b128 v[200:203], v146 offset:5120
	ds_read_b128 v[204:207], v146 offset:6144
	ds_read_b128 v[208:211], v146 offset:7168
	global_load_lds_dwordx4 v[212:213], off
	v_lshl_add_u64 v[212:213], v[144:145], 0, s[22:23]
	s_add_i32 m0, s9, 0xe000
	s_nop 0
	global_load_lds_dwordx4 v[212:213], off
	s_waitcnt vmcnt(8)
	s_waitcnt lgkmcnt(0)
	s_barrier
	s_setprio 1
	s_waitcnt lgkmcnt(0)
	v_mfma_f32_16x16x32_bf16 v[86:89], v[148:151], v[180:183], v[86:89]
	v_mfma_f32_16x16x32_bf16 v[82:85], v[156:159], v[180:183], v[82:85]
	v_mfma_f32_16x16x32_bf16 v[126:129], v[148:151], v[188:191], v[126:129]
	v_mfma_f32_16x16x32_bf16 v[110:113], v[156:159], v[188:191], v[110:113]
	v_mfma_f32_16x16x32_bf16 v[122:125], v[148:151], v[196:199], v[122:125]
	v_mfma_f32_16x16x32_bf16 v[118:121], v[156:159], v[196:199], v[118:121]
	v_mfma_f32_16x16x32_bf16 v[98:101], v[148:151], v[204:207], v[98:101]
	v_mfma_f32_16x16x32_bf16 v[94:97], v[156:159], v[204:207], v[94:97]
	v_mfma_f32_16x16x32_bf16 v[86:89], v[152:155], v[184:187], v[86:89]
	v_mfma_f32_16x16x32_bf16 v[82:85], v[160:163], v[184:187], v[82:85]
	v_mfma_f32_16x16x32_bf16 v[126:129], v[152:155], v[192:195], v[126:129]
	v_mfma_f32_16x16x32_bf16 v[110:113], v[160:163], v[192:195], v[110:113]
	v_mfma_f32_16x16x32_bf16 v[122:125], v[152:155], v[200:203], v[122:125]
	v_mfma_f32_16x16x32_bf16 v[118:121], v[160:163], v[200:203], v[118:121]
	v_mfma_f32_16x16x32_bf16 v[98:101], v[152:155], v[208:211], v[98:101]
	v_mfma_f32_16x16x32_bf16 v[94:97], v[160:163], v[208:211], v[94:97]
	s_setprio 0
	s_setprio 1
	v_mfma_f32_16x16x32_bf16 v[78:81], v[164:167], v[180:183], v[78:81]
	v_mfma_f32_16x16x32_bf16 v[74:77], v[172:175], v[180:183], v[74:77]
	v_mfma_f32_16x16x32_bf16 v[102:105], v[164:167], v[188:191], v[102:105]
	v_mfma_f32_16x16x32_bf16 v[90:93], v[172:175], v[188:191], v[90:93]
	v_mfma_f32_16x16x32_bf16 v[114:117], v[164:167], v[196:199], v[114:117]
	v_mfma_f32_16x16x32_bf16 v[106:109], v[172:175], v[196:199], v[106:109]
	v_mfma_f32_16x16x32_bf16 v[70:73], v[164:167], v[204:207], v[70:73]
	v_mfma_f32_16x16x32_bf16 v[66:69], v[172:175], v[204:207], v[66:69]
	v_mfma_f32_16x16x32_bf16 v[78:81], v[168:171], v[184:187], v[78:81]
	v_mfma_f32_16x16x32_bf16 v[74:77], v[176:179], v[184:187], v[74:77]
	v_mfma_f32_16x16x32_bf16 v[102:105], v[168:171], v[192:195], v[102:105]
	v_mfma_f32_16x16x32_bf16 v[90:93], v[176:179], v[192:195], v[90:93]
	v_mfma_f32_16x16x32_bf16 v[114:117], v[168:171], v[200:203], v[114:117]
	v_mfma_f32_16x16x32_bf16 v[106:109], v[176:179], v[200:203], v[106:109]
	v_mfma_f32_16x16x32_bf16 v[70:73], v[168:171], v[208:211], v[70:73]
	v_mfma_f32_16x16x32_bf16 v[66:69], v[176:179], v[208:211], v[66:69]
	s_setprio 0
	s_barrier
	s_add_i32 s51, s43, s36
	v_lshl_add_u64 v[212:213], s[24:25], 0, v[130:131]
	s_mov_b32 m0, s51
	ds_read_b128 v[180:183], v146 offset:16384
	ds_read_b128 v[184:187], v146 offset:17408
	ds_read_b128 v[188:191], v146 offset:18432
	ds_read_b128 v[192:195], v146 offset:19456
	ds_read_b128 v[196:199], v146 offset:20480
	ds_read_b128 v[200:203], v146 offset:21504
	ds_read_b128 v[204:207], v146 offset:22528
	ds_read_b128 v[208:211], v146 offset:23552
	global_load_lds_dwordx4 v[212:213], off
	s_add_i32 m0, s51, 0x2000
	s_add_u32 s52, s24, 0x80000
	v_lshl_add_u64 v[214:215], s[24:25], 0, v[132:133]
	s_addc_u32 s53, s25, 0
	s_add_i32 s51, s44, s36
	global_load_lds_dwordx4 v[214:215], off
	v_lshl_add_u64 v[216:217], s[52:53], 0, v[130:131]
	s_mov_b32 m0, s51
	v_lshl_add_u64 v[218:219], s[28:29], 0, v[132:133]
	global_load_lds_dwordx4 v[216:217], off
	v_lshl_add_u64 v[216:217], s[52:53], 0, v[132:133]
	s_add_i32 m0, s51, 0x2000
	s_nop 0
	global_load_lds_dwordx4 v[216:217], off
	v_lshl_add_u64 v[216:217], s[28:29], 0, v[130:131]
	s_mov_b32 m0, s9
	s_nop 0
	global_load_lds_dwordx4 v[216:217], off
	s_mov_b32 m0, s37
	s_nop 0
	global_load_lds_dwordx4 v[218:219], off
	s_waitcnt vmcnt(8)
	s_waitcnt lgkmcnt(0)
	s_barrier
	s_setprio 1
	s_waitcnt lgkmcnt(0)
	v_mfma_f32_16x16x32_bf16 v[62:65], v[148:151], v[180:183], v[62:65]
	v_mfma_f32_16x16x32_bf16 v[58:61], v[156:159], v[180:183], v[58:61]
	v_mfma_f32_16x16x32_bf16 v[46:49], v[148:151], v[188:191], v[46:49]
	v_mfma_f32_16x16x32_bf16 v[42:45], v[156:159], v[188:191], v[42:45]
	v_mfma_f32_16x16x32_bf16 v[30:33], v[148:151], v[196:199], v[30:33]
	v_mfma_f32_16x16x32_bf16 v[26:29], v[156:159], v[196:199], v[26:29]
	v_mfma_f32_16x16x32_bf16 v[14:17], v[148:151], v[204:207], v[14:17]
	v_mfma_f32_16x16x32_bf16 v[10:13], v[156:159], v[204:207], v[10:13]
	v_mfma_f32_16x16x32_bf16 v[62:65], v[152:155], v[184:187], v[62:65]
	v_mfma_f32_16x16x32_bf16 v[58:61], v[160:163], v[184:187], v[58:61]
	v_mfma_f32_16x16x32_bf16 v[46:49], v[152:155], v[192:195], v[46:49]
	v_mfma_f32_16x16x32_bf16 v[42:45], v[160:163], v[192:195], v[42:45]
	v_mfma_f32_16x16x32_bf16 v[30:33], v[152:155], v[200:203], v[30:33]
	v_mfma_f32_16x16x32_bf16 v[26:29], v[160:163], v[200:203], v[26:29]
	v_mfma_f32_16x16x32_bf16 v[14:17], v[152:155], v[208:211], v[14:17]
	v_mfma_f32_16x16x32_bf16 v[10:13], v[160:163], v[208:211], v[10:13]
	s_setprio 0
	s_setprio 1
	v_mfma_f32_16x16x32_bf16 v[54:57], v[164:167], v[180:183], v[54:57]
	v_mfma_f32_16x16x32_bf16 v[50:53], v[172:175], v[180:183], v[50:53]
	v_mfma_f32_16x16x32_bf16 v[38:41], v[164:167], v[188:191], v[38:41]
	v_mfma_f32_16x16x32_bf16 v[34:37], v[172:175], v[188:191], v[34:37]
	v_mfma_f32_16x16x32_bf16 v[22:25], v[164:167], v[196:199], v[22:25]
	v_mfma_f32_16x16x32_bf16 v[18:21], v[172:175], v[196:199], v[18:21]
	v_mfma_f32_16x16x32_bf16 v[6:9], v[164:167], v[204:207], v[6:9]
	v_mfma_f32_16x16x32_bf16 v[2:5], v[172:175], v[204:207], v[2:5]
	v_mfma_f32_16x16x32_bf16 v[54:57], v[168:171], v[184:187], v[54:57]
	v_mfma_f32_16x16x32_bf16 v[50:53], v[176:179], v[184:187], v[50:53]
	v_mfma_f32_16x16x32_bf16 v[38:41], v[168:171], v[192:195], v[38:41]
	v_mfma_f32_16x16x32_bf16 v[34:37], v[176:179], v[192:195], v[34:37]
	v_mfma_f32_16x16x32_bf16 v[22:25], v[168:171], v[200:203], v[22:25]
	v_mfma_f32_16x16x32_bf16 v[18:21], v[176:179], v[200:203], v[18:21]
	v_mfma_f32_16x16x32_bf16 v[6:9], v[168:171], v[208:211], v[6:9]
	v_mfma_f32_16x16x32_bf16 v[2:5], v[176:179], v[208:211], v[2:5]
	s_setprio 0
	s_barrier
	s_add_i32 s51, 0, 0x18000
	v_add_u32_e32 v147, s51, v1
	s_add_i32 s52, 0, 0x1c000
	ds_read_b128 v[148:151], v147
	ds_read_b128 v[152:155], v147 offset:1024
	ds_read_b128 v[156:159], v147 offset:2048
	ds_read_b128 v[160:163], v147 offset:3072
	v_add_u32_e32 v147, s52, v1
	ds_read_b128 v[164:167], v147
	ds_read_b128 v[168:171], v147 offset:1024
	ds_read_b128 v[172:175], v147 offset:2048
	ds_read_b128 v[176:179], v147 offset:3072
	s_add_u32 s28, s28, 0x80000
	s_addc_u32 s29, s29, 0
	s_mov_b32 m0, s38
	v_lshl_add_u64 v[220:221], s[28:29], 0, v[130:131]
	ds_read_b128 v[180:183], v146 offset:32768
	ds_read_b128 v[184:187], v146 offset:33792
	ds_read_b128 v[188:191], v146 offset:34816
	ds_read_b128 v[192:195], v146 offset:35840
	ds_read_b128 v[196:199], v146 offset:36864
	ds_read_b128 v[200:203], v146 offset:37888
	ds_read_b128 v[204:207], v146 offset:38912
	ds_read_b128 v[208:211], v146 offset:39936
	global_load_lds_dwordx4 v[220:221], off
	v_lshl_add_u64 v[220:221], s[28:29], 0, v[132:133]
	s_mov_b32 m0, s39
	s_nop 0
	global_load_lds_dwordx4 v[220:221], off
	s_waitcnt vmcnt(8)
	s_waitcnt lgkmcnt(0)
	s_barrier
	s_setprio 1
	s_waitcnt lgkmcnt(0)
	v_mfma_f32_16x16x32_bf16 v[86:89], v[148:151], v[180:183], v[86:89]
	v_mfma_f32_16x16x32_bf16 v[82:85], v[156:159], v[180:183], v[82:85]
	v_mfma_f32_16x16x32_bf16 v[126:129], v[148:151], v[188:191], v[126:129]
	v_mfma_f32_16x16x32_bf16 v[110:113], v[156:159], v[188:191], v[110:113]
	v_mfma_f32_16x16x32_bf16 v[122:125], v[148:151], v[196:199], v[122:125]
	v_mfma_f32_16x16x32_bf16 v[118:121], v[156:159], v[196:199], v[118:121]
	v_mfma_f32_16x16x32_bf16 v[98:101], v[148:151], v[204:207], v[98:101]
	v_mfma_f32_16x16x32_bf16 v[94:97], v[156:159], v[204:207], v[94:97]
	v_mfma_f32_16x16x32_bf16 v[86:89], v[152:155], v[184:187], v[86:89]
	v_mfma_f32_16x16x32_bf16 v[82:85], v[160:163], v[184:187], v[82:85]
	v_mfma_f32_16x16x32_bf16 v[126:129], v[152:155], v[192:195], v[126:129]
	v_mfma_f32_16x16x32_bf16 v[110:113], v[160:163], v[192:195], v[110:113]
	v_mfma_f32_16x16x32_bf16 v[122:125], v[152:155], v[200:203], v[122:125]
	v_mfma_f32_16x16x32_bf16 v[118:121], v[160:163], v[200:203], v[118:121]
	v_mfma_f32_16x16x32_bf16 v[98:101], v[152:155], v[208:211], v[98:101]
	v_mfma_f32_16x16x32_bf16 v[94:97], v[160:163], v[208:211], v[94:97]
	s_setprio 0
	s_setprio 1
	v_mfma_f32_16x16x32_bf16 v[78:81], v[164:167], v[180:183], v[78:81]
	v_mfma_f32_16x16x32_bf16 v[74:77], v[172:175], v[180:183], v[74:77]
	v_mfma_f32_16x16x32_bf16 v[102:105], v[164:167], v[188:191], v[102:105]
	v_mfma_f32_16x16x32_bf16 v[90:93], v[172:175], v[188:191], v[90:93]
	v_mfma_f32_16x16x32_bf16 v[114:117], v[164:167], v[196:199], v[114:117]
	v_mfma_f32_16x16x32_bf16 v[106:109], v[172:175], v[196:199], v[106:109]
	v_mfma_f32_16x16x32_bf16 v[70:73], v[164:167], v[204:207], v[70:73]
	v_mfma_f32_16x16x32_bf16 v[66:69], v[172:175], v[204:207], v[66:69]
	v_mfma_f32_16x16x32_bf16 v[78:81], v[168:171], v[184:187], v[78:81]
	v_mfma_f32_16x16x32_bf16 v[74:77], v[176:179], v[184:187], v[74:77]
	v_mfma_f32_16x16x32_bf16 v[102:105], v[168:171], v[192:195], v[102:105]
	v_mfma_f32_16x16x32_bf16 v[90:93], v[176:179], v[192:195], v[90:93]
	v_mfma_f32_16x16x32_bf16 v[114:117], v[168:171], v[200:203], v[114:117]
	v_mfma_f32_16x16x32_bf16 v[106:109], v[176:179], v[200:203], v[106:109]
	v_mfma_f32_16x16x32_bf16 v[70:73], v[168:171], v[208:211], v[70:73]
	v_mfma_f32_16x16x32_bf16 v[66:69], v[176:179], v[208:211], v[66:69]
	s_setprio 0
	s_barrier
	s_add_i32 s28, s51, s36
	v_lshl_add_u64 v[212:213], v[212:213], 0, s[12:13]
	s_mov_b32 m0, s28
	ds_read_b128 v[180:183], v146 offset:49152
	ds_read_b128 v[184:187], v146 offset:50176
	ds_read_b128 v[188:191], v146 offset:51200
	ds_read_b128 v[192:195], v146 offset:52224
	ds_read_b128 v[196:199], v146 offset:53248
	ds_read_b128 v[200:203], v146 offset:54272
	ds_read_b128 v[204:207], v146 offset:55296
	ds_read_b128 v[208:211], v146 offset:56320
	global_load_lds_dwordx4 v[212:213], off
	s_add_i32 m0, s28, 0x2000
	s_add_u32 s24, s24, 0x80080
	v_lshl_add_u64 v[212:213], v[214:215], 0, s[12:13]
	s_addc_u32 s25, s25, 0
	s_add_i32 s28, s52, s36
	global_load_lds_dwordx4 v[212:213], off
	v_lshl_add_u64 v[212:213], s[24:25], 0, v[130:131]
	s_mov_b32 m0, s28
	s_nop 0
	global_load_lds_dwordx4 v[212:213], off
	v_lshl_add_u64 v[212:213], s[24:25], 0, v[132:133]
	s_add_i32 m0, s28, 0x2000
	s_nop 0
	global_load_lds_dwordx4 v[212:213], off
	v_lshl_add_u64 v[212:213], v[216:217], 0, s[12:13]
	s_mov_b32 m0, s41
	s_nop 0
	global_load_lds_dwordx4 v[212:213], off
	v_lshl_add_u64 v[212:213], v[218:219], 0, s[12:13]
	s_mov_b32 m0, s42
	s_nop 0
	global_load_lds_dwordx4 v[212:213], off
	s_waitcnt vmcnt(8)
	s_waitcnt lgkmcnt(0)
	s_barrier
	s_setprio 1
	s_waitcnt lgkmcnt(0)
	v_mfma_f32_16x16x32_bf16 v[62:65], v[148:151], v[180:183], v[62:65]
	v_mfma_f32_16x16x32_bf16 v[58:61], v[156:159], v[180:183], v[58:61]
	v_mfma_f32_16x16x32_bf16 v[46:49], v[148:151], v[188:191], v[46:49]
	v_mfma_f32_16x16x32_bf16 v[42:45], v[156:159], v[188:191], v[42:45]
	v_mfma_f32_16x16x32_bf16 v[30:33], v[148:151], v[196:199], v[30:33]
	v_mfma_f32_16x16x32_bf16 v[26:29], v[156:159], v[196:199], v[26:29]
	v_mfma_f32_16x16x32_bf16 v[14:17], v[148:151], v[204:207], v[14:17]
	v_mfma_f32_16x16x32_bf16 v[10:13], v[156:159], v[204:207], v[10:13]
	v_mfma_f32_16x16x32_bf16 v[62:65], v[152:155], v[184:187], v[62:65]
	v_mfma_f32_16x16x32_bf16 v[58:61], v[160:163], v[184:187], v[58:61]
	v_mfma_f32_16x16x32_bf16 v[46:49], v[152:155], v[192:195], v[46:49]
	v_mfma_f32_16x16x32_bf16 v[42:45], v[160:163], v[192:195], v[42:45]
	v_mfma_f32_16x16x32_bf16 v[30:33], v[152:155], v[200:203], v[30:33]
	v_mfma_f32_16x16x32_bf16 v[26:29], v[160:163], v[200:203], v[26:29]
	v_mfma_f32_16x16x32_bf16 v[14:17], v[152:155], v[208:211], v[14:17]
	v_mfma_f32_16x16x32_bf16 v[10:13], v[160:163], v[208:211], v[10:13]
	s_setprio 0
	s_setprio 1
	v_mfma_f32_16x16x32_bf16 v[54:57], v[164:167], v[180:183], v[54:57]
	v_mfma_f32_16x16x32_bf16 v[50:53], v[172:175], v[180:183], v[50:53]
	v_mfma_f32_16x16x32_bf16 v[38:41], v[164:167], v[188:191], v[38:41]
	v_mfma_f32_16x16x32_bf16 v[34:37], v[172:175], v[188:191], v[34:37]
	v_mfma_f32_16x16x32_bf16 v[22:25], v[164:167], v[196:199], v[22:25]
	v_mfma_f32_16x16x32_bf16 v[18:21], v[172:175], v[196:199], v[18:21]
	v_mfma_f32_16x16x32_bf16 v[6:9], v[164:167], v[204:207], v[6:9]
	v_mfma_f32_16x16x32_bf16 v[2:5], v[172:175], v[204:207], v[2:5]
	v_mfma_f32_16x16x32_bf16 v[54:57], v[168:171], v[184:187], v[54:57]
	v_mfma_f32_16x16x32_bf16 v[50:53], v[176:179], v[184:187], v[50:53]
	v_mfma_f32_16x16x32_bf16 v[38:41], v[168:171], v[192:195], v[38:41]
	v_mfma_f32_16x16x32_bf16 v[34:37], v[176:179], v[192:195], v[34:37]
	v_mfma_f32_16x16x32_bf16 v[22:25], v[168:171], v[200:203], v[22:25]
	v_mfma_f32_16x16x32_bf16 v[18:21], v[176:179], v[200:203], v[18:21]
	v_mfma_f32_16x16x32_bf16 v[6:9], v[168:171], v[208:211], v[6:9]
	v_mfma_f32_16x16x32_bf16 v[2:5], v[176:179], v[208:211], v[2:5]
	s_add_i32 s50, s50, 2
	s_add_u32 s22, s22, 0x100
	s_addc_u32 s23, s23, 0
	s_cmp_gt_u32 s50, 29
	s_setprio 0
	s_barrier
	s_cbranch_scc0 .LBB0_1174
	s_add_u32 s22, s46, 0xffffff00
	s_addc_u32 s23, s47, -1
	s_andn2_b64 vcc, exec, s[2:3]
	s_cbranch_vccnz .LBB0_1177
	v_mov_b32_e32 v2, 0
	s_mov_b32 s4, s14
	s_mov_b32 s8, s16
	s_mov_b64 s[10:11], s[20:21]
	s_mov_b32 s40, s45
	v_mov_b32_e32 v3, 0
	v_mov_b64_e32 v[4:5], 0
	v_mov_b64_e32 v[6:7], 0
	v_mov_b64_e32 v[8:9], 0
	v_mov_b64_e32 v[10:11], 0
	v_mov_b64_e32 v[12:13], 0
	v_mov_b64_e32 v[14:15], 0
	v_mov_b64_e32 v[16:17], 0
	v_mov_b64_e32 v[18:19], 0
	v_mov_b64_e32 v[20:21], 0
	v_mov_b64_e32 v[22:23], 0
	v_mov_b64_e32 v[24:25], 0
	v_mov_b64_e32 v[26:27], 0
	v_mov_b64_e32 v[28:29], 0
	v_mov_b64_e32 v[30:31], 0
	v_mov_b64_e32 v[32:33], 0
	v_mov_b64_e32 v[34:35], 0
	v_mov_b64_e32 v[36:37], 0
	v_mov_b64_e32 v[38:39], 0
	v_mov_b64_e32 v[40:41], 0
	v_mov_b64_e32 v[42:43], 0
	v_mov_b64_e32 v[44:45], 0
	v_mov_b64_e32 v[46:47], 0
	v_mov_b64_e32 v[48:49], 0
	v_mov_b64_e32 v[50:51], 0
	v_mov_b64_e32 v[52:53], 0
	v_mov_b64_e32 v[54:55], 0
	v_mov_b64_e32 v[56:57], 0
	v_mov_b64_e32 v[58:59], 0
	v_mov_b64_e32 v[60:61], 0
	v_mov_b64_e32 v[62:63], 0
	v_mov_b64_e32 v[64:65], 0
	v_mov_b64_e32 v[66:67], 0
	v_mov_b64_e32 v[68:69], 0
	v_mov_b64_e32 v[70:71], 0
	v_mov_b64_e32 v[72:73], 0
	v_mov_b64_e32 v[74:75], 0
	v_mov_b64_e32 v[76:77], 0
	v_mov_b64_e32 v[78:79], 0
	v_mov_b64_e32 v[80:81], 0
	v_mov_b64_e32 v[82:83], 0
	v_mov_b64_e32 v[84:85], 0
	v_mov_b64_e32 v[86:87], 0
	v_mov_b64_e32 v[88:89], 0
	v_mov_b64_e32 v[90:91], 0
	v_mov_b64_e32 v[92:93], 0
	v_mov_b64_e32 v[94:95], 0
	v_mov_b64_e32 v[96:97], 0
	v_mov_b64_e32 v[98:99], 0
	v_mov_b64_e32 v[100:101], 0
	v_mov_b64_e32 v[102:103], 0
	v_mov_b64_e32 v[104:105], 0
	v_mov_b64_e32 v[106:107], 0
	v_mov_b64_e32 v[108:109], 0
	v_mov_b64_e32 v[110:111], 0
	v_mov_b64_e32 v[112:113], 0
	v_mov_b64_e32 v[114:115], 0
	v_mov_b64_e32 v[116:117], 0
	v_mov_b64_e32 v[118:119], 0
	v_mov_b64_e32 v[120:121], 0
	v_mov_b64_e32 v[122:123], 0
	v_mov_b64_e32 v[124:125], 0
	v_mov_b64_e32 v[126:127], 0
	v_mov_b64_e32 v[128:129], 0
	s_andn2_b64 vcc, exec, s[0:1]
	s_cbranch_vccnz .LBB0_1178
	s_branch .LBB0_1179
